# attention loops: dead exchange-index computation and redundant canonicalising max / zero-add ops removed
# speedup vs baseline: 1.0033x; 1.0033x over previous
.LBB0_347:
	s_bitcmp1_b32 s85, 0
	s_cselect_b32 s3, 0x2c00, 0
	s_cmp_gt_i32 s85, s97
	s_mov_b64 s[86:87], -1
	s_cbranch_scc1 .LBB0_435
	v_add_u32_e32 v2, s85, v195
	v_cmp_ge_u32_e32 vcc, v2, v194
	v_cmp_lt_u32_e64 s[86:87], v2, v214
	v_mov_b32_e32 v221, v163
	v_mov_b32_e32 v166, v0
	v_mov_b32_e32 v222, v220
	v_mov_b32_e32 v162, v219
	s_and_b64 vcc, vcc, s[86:87]
	s_and_saveexec_b64 s[86:87], vcc
	s_cbranch_execz .LBB0_434
	v_lshl_add_u32 v162, s3, 1, v215
	v_mov_b32_e32 v189, 0xff800000
	ds_read2_b32 v[168:169], v218 offset0:8 offset1:9
	ds_read2_b32 v[170:171], v218 offset0:10 offset1:11
	ds_read2_b32 v[172:173], v218 offset0:16 offset1:17
	ds_read2_b32 v[174:175], v218 offset0:18 offset1:19
	ds_read2_b32 v[176:177], v218 offset0:24 offset1:25
	ds_read2_b32 v[178:179], v218 offset0:26 offset1:27
	ds_read2_b32 v[180:181], v218 offset0:32 offset1:33
	ds_read2_b32 v[182:183], v218 offset0:34 offset1:35
	ds_read2_b32 v[22:23], v218 offset0:40 offset1:41
	ds_read2_b32 v[24:25], v218 offset0:42 offset1:43
	ds_read2_b32 v[18:19], v218 offset0:0 offset1:1
	ds_read2_b32 v[20:21], v218 offset0:2 offset1:3
	ds_read_b128 v[2:5], v162
	ds_read_b128 v[184:187], v162 offset:32
	ds_read_b128 v[54:57], v192 offset:47104
	ds_read_b128 v[58:61], v192 offset:47136
	s_waitcnt lgkmcnt(3)
	v_mfma_f32_32x32x16_bf16 v[38:53], v[2:5], v[130:133], v[168:183]
	s_waitcnt lgkmcnt(1)
	v_mfma_f32_32x32x16_bf16 v[6:21], v[2:5], v[54:57], v[6:21]
	ds_read_b128 v[2:5], v162 offset:64
	ds_read_b128 v[62:65], v192 offset:47168
	v_mfma_f32_32x32x16_bf16 v[38:53], v[184:187], v[134:137], v[38:53]
	s_waitcnt lgkmcnt(2)
	v_mfma_f32_32x32x16_bf16 v[6:21], v[184:187], v[58:61], v[6:21]
	s_waitcnt lgkmcnt(1)
	v_mfma_f32_32x32x16_bf16 v[38:53], v[2:5], v[138:141], v[38:53]
	s_waitcnt lgkmcnt(0)
	v_mfma_f32_32x32x16_bf16 v[6:21], v[2:5], v[62:65], v[6:21]
	ds_read_b128 v[2:5], v162 offset:96
	ds_read_b128 v[164:167], v192 offset:47200
	s_waitcnt lgkmcnt(1)
	v_mfma_f32_32x32x16_bf16 v[38:53], v[2:5], v[142:145], v[38:53]
	s_waitcnt lgkmcnt(0)
	v_mfma_f32_32x32x16_bf16 v[6:21], v[2:5], v[164:167], v[6:21]
	ds_read_b128 v[2:5], v162 offset:4608
	s_waitcnt lgkmcnt(0)
	v_mfma_f32_32x32x16_bf16 v[22:37], v[2:5], v[130:133], v[22:37]
	v_mfma_f32_32x32x16_bf16 v[2:17], v[2:5], v[54:57], v[168:183]
	ds_read_b128 v[54:57], v162 offset:4640
	s_waitcnt lgkmcnt(0)
	v_mfma_f32_32x32x16_bf16 v[22:37], v[54:57], v[134:137], v[22:37]
	v_mfma_f32_32x32x16_bf16 v[2:17], v[54:57], v[58:61], v[2:17]
	ds_read_b128 v[54:57], v162 offset:4672
	s_waitcnt lgkmcnt(0)
	v_mfma_f32_32x32x16_bf16 v[22:37], v[54:57], v[138:141], v[22:37]
	v_mfma_f32_32x32x16_bf16 v[2:17], v[54:57], v[62:65], v[2:17]
	ds_read_b128 v[54:57], v162 offset:4704
	s_waitcnt lgkmcnt(0)
	v_mfma_f32_32x32x16_bf16 v[22:37], v[54:57], v[142:145], v[22:37]
	v_mfma_f32_32x32x16_bf16 v[2:17], v[54:57], v[164:167], v[2:17]
	v_cndmask_b32_e64 v164, v189, v46, s[18:19]
	v_cndmask_b32_e64 v162, v189, v47, s[20:21]
	v_cndmask_b32_e64 v177, v189, v48, s[22:23]
	v_cndmask_b32_e64 v178, v189, v49, s[24:25]
	v_cndmask_b32_e64 v179, v189, v50, s[26:27]
	v_cndmask_b32_e64 v166, v189, v51, s[28:29]
	v_cndmask_b32_e64 v181, v189, v52, s[30:31]
	v_cndmask_b32_e64 v182, v189, v53, s[34:35]
	s_nop 2
	v_cndmask_b32_e64 v27, v189, v38, s[0:1]
	v_cndmask_b32_e64 v26, v189, v39, s[4:5]
	v_cndmask_b32_e64 v29, v189, v40, s[6:7]
	v_cndmask_b32_e64 v28, v189, v41, s[8:9]
	v_cndmask_b32_e64 v31, v189, v42, s[10:11]
	v_cndmask_b32_e64 v30, v189, v43, s[12:13]
	v_cndmask_b32_e64 v33, v189, v44, s[14:15]
	v_cndmask_b32_e64 v32, v189, v45, s[16:17]
	v_cndmask_b32_e64 v183, v189, v22, s[36:37]
	v_cndmask_b32_e64 v184, v189, v23, s[38:39]
	v_cndmask_b32_e64 v185, v189, v24, s[40:41]
	v_cndmask_b32_e64 v23, v189, v25, s[42:43]
	v_max3_f32 v24, v27, v26, v29
	v_max3_f32 v24, v24, v28, v31
	v_max3_f32 v24, v24, v30, v33
	v_max3_f32 v24, v24, v32, v164
	v_max3_f32 v24, v24, v162, v177
	v_max3_f32 v24, v24, v178, v179
	v_max3_f32 v24, v24, v166, v181
	v_max3_f32 v24, v24, v182, v183
	v_max3_f32 v24, v24, v184, v185
	s_mov_b32 s88, 0xff800000
	v_max3_f32 v24, v24, v23, s88
	v_mov_b32_e32 v25, v24
	s_nop 1
	v_permlane32_swap_b32_e32 v24, v25
	v_max_f32_e32 v25, v25, v25
	v_max_f32_e32 v24, v24, v25
	v_add_f32_e32 v25, 0xc1000000, v24
	v_cmp_gt_f32_e32 vcc, v25, v163
	v_mov_b32_e32 v165, v220
	v_mov_b32_e32 v221, v163
	s_cbranch_vccz .LBB0_391
	v_max_f32_e32 v24, v24, v24
	v_max_f32_e32 v25, v163, v163
	v_max_f32_e32 v221, v25, v24
	v_sub_f32_e32 v24, v163, v221
	v_exp_f32_e32 v24, v24
	s_nop 0
	v_mul_f32_e32 v165, v220, v24
	v_pk_mul_f32 v[128:129], v[128:129], v[24:25] op_sel_hi:[1,0]
	v_pk_mul_f32 v[126:127], v[126:127], v[24:25] op_sel_hi:[1,0]
	v_pk_mul_f32 v[124:125], v[124:125], v[24:25] op_sel_hi:[1,0]
	v_pk_mul_f32 v[122:123], v[122:123], v[24:25] op_sel_hi:[1,0]
	v_pk_mul_f32 v[120:121], v[120:121], v[24:25] op_sel_hi:[1,0]
	v_pk_mul_f32 v[118:119], v[118:119], v[24:25] op_sel_hi:[1,0]
	v_pk_mul_f32 v[116:117], v[116:117], v[24:25] op_sel_hi:[1,0]
	v_pk_mul_f32 v[114:115], v[114:115], v[24:25] op_sel_hi:[1,0]
	v_pk_mul_f32 v[112:113], v[112:113], v[24:25] op_sel_hi:[1,0]
	v_pk_mul_f32 v[110:111], v[110:111], v[24:25] op_sel_hi:[1,0]
	v_pk_mul_f32 v[108:109], v[108:109], v[24:25] op_sel_hi:[1,0]
	v_pk_mul_f32 v[106:107], v[106:107], v[24:25] op_sel_hi:[1,0]
	v_pk_mul_f32 v[104:105], v[104:105], v[24:25] op_sel_hi:[1,0]
	v_pk_mul_f32 v[102:103], v[102:103], v[24:25] op_sel_hi:[1,0]
	v_pk_mul_f32 v[100:101], v[100:101], v[24:25] op_sel_hi:[1,0]
	v_pk_mul_f32 v[98:99], v[98:99], v[24:25] op_sel_hi:[1,0]

.LBB0_746:
	s_bitcmp1_b32 s11, 0
	s_cselect_b32 s12, 0x2c00, 0
	s_lshl_b32 s13, s12, 1
	v_add3_u32 v15, v192, s13, v191
	ds_read_b128 v[2:5], v15
	ds_read_b128 v[10:13], v194 offset:47104
	ds_read_b128 v[240:243], v15 offset:32
	ds_read_b128 v[216:219], v194 offset:47136
	ds_read_b128 v[244:247], v15 offset:64
	ds_read_b128 v[6:9], v194 offset:47168
	ds_read_b128 v[248:251], v15 offset:96
	ds_read_b128 v[220:223], v194 offset:47200
	s_waitcnt lgkmcnt(7)
	v_mfma_f32_32x32x16_bf16 v[112:127], v[2:5], v[144:147], 0
	s_waitcnt lgkmcnt(6)
	v_mfma_f32_32x32x16_bf16 v[96:111], v[2:5], v[10:13], 0
	ds_read_b128 v[2:5], v15 offset:128
	ds_read_b128 v[224:227], v194 offset:47232
	s_waitcnt lgkmcnt(7)
	v_mfma_f32_32x32x16_bf16 v[112:127], v[240:243], v[148:151], v[112:127]
	s_waitcnt lgkmcnt(6)
	v_mfma_f32_32x32x16_bf16 v[96:111], v[240:243], v[216:219], v[96:111]
	ds_read_b128 v[240:243], v15 offset:160
	ds_read_b128 v[228:231], v194 offset:47264
	s_waitcnt lgkmcnt(7)
	v_mfma_f32_32x32x16_bf16 v[112:127], v[244:247], v[152:155], v[112:127]
	s_waitcnt lgkmcnt(6)
	v_mfma_f32_32x32x16_bf16 v[96:111], v[244:247], v[6:9], v[96:111]
	ds_read_b128 v[244:247], v15 offset:6656
	s_waitcnt lgkmcnt(6)
	v_mfma_f32_32x32x16_bf16 v[112:127], v[248:251], v[156:159], v[112:127]
	s_waitcnt lgkmcnt(5)
	v_mfma_f32_32x32x16_bf16 v[96:111], v[248:251], v[220:223], v[96:111]
	ds_read_b128 v[248:251], v15 offset:6688
	s_waitcnt lgkmcnt(5)
	v_mfma_f32_32x32x16_bf16 v[112:127], v[2:5], v[160:163], v[112:127]
	s_waitcnt lgkmcnt(4)
	v_mfma_f32_32x32x16_bf16 v[96:111], v[2:5], v[224:227], v[96:111]
	ds_read_b128 v[2:5], v15 offset:6720
	s_waitcnt lgkmcnt(4)
	v_mfma_f32_32x32x16_bf16 v[112:127], v[240:243], v[164:167], v[112:127]
	s_waitcnt lgkmcnt(3)
	v_mfma_f32_32x32x16_bf16 v[96:111], v[240:243], v[228:231], v[96:111]
	ds_read_b128 v[240:243], v15 offset:6752
	s_waitcnt lgkmcnt(3)
	v_mfma_f32_32x32x16_bf16 v[128:143], v[244:247], v[144:147], 0
	v_mfma_f32_32x32x16_bf16 v[80:95], v[244:247], v[10:13], 0
	ds_read_b128 v[244:247], v15 offset:6784
	s_waitcnt lgkmcnt(3)
	v_mfma_f32_32x32x16_bf16 v[128:143], v[248:251], v[148:151], v[128:143]
	v_mfma_f32_32x32x16_bf16 v[80:95], v[248:251], v[216:219], v[80:95]
	ds_read_b128 v[248:251], v15 offset:6816
	s_waitcnt lgkmcnt(3)
	v_mfma_f32_32x32x16_bf16 v[128:143], v[2:5], v[152:155], v[128:143]
	v_mfma_f32_32x32x16_bf16 v[80:95], v[2:5], v[6:9], v[80:95]
	s_waitcnt lgkmcnt(2)
	v_mfma_f32_32x32x16_bf16 v[128:143], v[240:243], v[156:159], v[128:143]
	v_mfma_f32_32x32x16_bf16 v[80:95], v[240:243], v[220:223], v[80:95]
	s_waitcnt lgkmcnt(1)
	v_mfma_f32_32x32x16_bf16 v[128:143], v[244:247], v[160:163], v[128:143]
	v_mfma_f32_32x32x16_bf16 v[80:95], v[244:247], v[224:227], v[80:95]
	s_waitcnt lgkmcnt(0)
	v_mfma_f32_32x32x16_bf16 v[128:143], v[248:251], v[164:167], v[128:143]
	v_mfma_f32_32x32x16_bf16 v[80:95], v[248:251], v[228:231], v[80:95]
	v_max_f32_e32 v2, v112, v113
	v_max3_f32 v2, v2, v114, v115
	v_max3_f32 v2, v2, v116, v117
	v_max3_f32 v2, v2, v118, v119
	v_max3_f32 v2, v2, v120, v121
	v_max3_f32 v2, v2, v122, v123
	v_max3_f32 v2, v2, v124, v125
	v_max3_f32 v2, v2, v126, v127
	s_nop 2
	v_max3_f32 v2, v2, v128, v129
	v_max3_f32 v2, v2, v130, v131
	v_max3_f32 v2, v2, v132, v133
	v_max3_f32 v2, v2, v134, v135
	v_max3_f32 v2, v2, v136, v137
	v_max3_f32 v2, v2, v138, v139
	v_max3_f32 v2, v2, v140, v141
	v_max3_f32 v2, v2, v142, v143
	v_mov_b32_e32 v3, v2
	s_nop 1
	v_permlane32_swap_b32_e32 v2, v3
	v_max_f32_e32 v2, v2, v3
	v_add_f32_e32 v3, 0xc1000000, v2
	v_cmp_gt_f32_e32 vcc, v3, v215
	s_cbranch_vccz .LBB0_748
	v_max_f32_e32 v2, v2, v2
	v_max_f32_e32 v3, v215, v215
	v_max_f32_e32 v3, v3, v2
	v_sub_f32_e32 v2, v215, v3
	v_exp_f32_e32 v2, v2
	v_mov_b32_e32 v215, v3
	v_mul_f32_e32 v0, v0, v2
	v_pk_mul_f32 v[78:79], v[78:79], v[2:3] op_sel_hi:[1,0]
	v_pk_mul_f32 v[76:77], v[76:77], v[2:3] op_sel_hi:[1,0]
	v_pk_mul_f32 v[74:75], v[74:75], v[2:3] op_sel_hi:[1,0]
	v_pk_mul_f32 v[72:73], v[72:73], v[2:3] op_sel_hi:[1,0]
	v_pk_mul_f32 v[70:71], v[70:71], v[2:3] op_sel_hi:[1,0]
	v_pk_mul_f32 v[68:69], v[68:69], v[2:3] op_sel_hi:[1,0]
	v_pk_mul_f32 v[66:67], v[66:67], v[2:3] op_sel_hi:[1,0]
	v_pk_mul_f32 v[64:65], v[64:65], v[2:3] op_sel_hi:[1,0]
	v_pk_mul_f32 v[62:63], v[62:63], v[2:3] op_sel_hi:[1,0]
	v_pk_mul_f32 v[60:61], v[60:61], v[2:3] op_sel_hi:[1,0]
	v_pk_mul_f32 v[58:59], v[58:59], v[2:3] op_sel_hi:[1,0]
	v_pk_mul_f32 v[56:57], v[56:57], v[2:3] op_sel_hi:[1,0]
	v_pk_mul_f32 v[54:55], v[54:55], v[2:3] op_sel_hi:[1,0]
	v_pk_mul_f32 v[52:53], v[52:53], v[2:3] op_sel_hi:[1,0]
	v_pk_mul_f32 v[50:51], v[50:51], v[2:3] op_sel_hi:[1,0]
	v_pk_mul_f32 v[48:49], v[48:49], v[2:3] op_sel_hi:[1,0]
.LBB0_748:
	v_lshl_add_u32 v202, s12, 1, v214
	v_add_u32_e32 v203, 0x3000, v202
	v_add_u32_e32 v208, 0x4000, v202
	ds_read2_b64 v[6:9], v203 offset0:128 offset1:130
	ds_read2_b64 v[2:5], v203 offset0:132 offset1:134
	ds_read2_b64 v[10:13], v208 offset0:192 offset1:194
	v_sub_f32_e32 v112, v112, v215
	v_sub_f32_e32 v113, v113, v215
	v_sub_f32_e32 v114, v114, v215
	v_sub_f32_e32 v115, v115, v215
	v_sub_f32_e32 v116, v116, v215
	v_sub_f32_e32 v117, v117, v215
	v_sub_f32_e32 v118, v118, v215
	v_sub_f32_e32 v119, v119, v215
	v_exp_f32_e32 v15, v112
	v_exp_f32_e32 v216, v113
	v_exp_f32_e32 v217, v114
	v_exp_f32_e32 v218, v115
	v_exp_f32_e32 v219, v116
	v_exp_f32_e32 v220, v117
	v_exp_f32_e32 v221, v118
	v_exp_f32_e32 v222, v119
	v_sub_f32_e32 v120, v120, v215
	v_sub_f32_e32 v121, v121, v215
	v_sub_f32_e32 v122, v122, v215
	v_sub_f32_e32 v123, v123, v215
	v_sub_f32_e32 v124, v124, v215
	v_sub_f32_e32 v125, v125, v215
	v_sub_f32_e32 v126, v126, v215
	v_sub_f32_e32 v127, v127, v215
	v_exp_f32_e32 v223, v120
	v_exp_f32_e32 v224, v121
	v_exp_f32_e32 v225, v122
	v_exp_f32_e32 v226, v123
	v_exp_f32_e32 v227, v124
	v_exp_f32_e32 v228, v125
	v_exp_f32_e32 v229, v126
	v_exp_f32_e32 v230, v127
	v_sub_f32_e32 v128, v128, v215
	v_sub_f32_e32 v129, v129, v215
	v_sub_f32_e32 v130, v130, v215
	v_sub_f32_e32 v131, v131, v215
	v_sub_f32_e32 v132, v132, v215
	v_sub_f32_e32 v133, v133, v215
	v_sub_f32_e32 v134, v134, v215
	v_sub_f32_e32 v135, v135, v215
	v_exp_f32_e32 v231, v128
	v_exp_f32_e32 v232, v129
	v_exp_f32_e32 v233, v130
	v_exp_f32_e32 v234, v131
	v_exp_f32_e32 v132, v132
	v_exp_f32_e32 v133, v133
	v_exp_f32_e32 v134, v134
	v_exp_f32_e32 v135, v135
	v_sub_f32_e32 v136, v136, v215
	v_sub_f32_e32 v137, v137, v215
	v_sub_f32_e32 v138, v138, v215
	v_sub_f32_e32 v139, v139, v215
	v_sub_f32_e32 v140, v140, v215
	v_sub_f32_e32 v141, v141, v215
	v_sub_f32_e32 v142, v142, v215
	v_sub_f32_e32 v143, v143, v215
	v_exp_f32_e32 v136, v136
	v_exp_f32_e32 v137, v137
	v_exp_f32_e32 v138, v138
	v_exp_f32_e32 v139, v139
	v_exp_f32_e32 v140, v140
	v_exp_f32_e32 v141, v141
	v_exp_f32_e32 v142, v142
	v_exp_f32_e32 v143, v143
	v_mov_b32_e32 v128, v203
	v_mov_b32_e32 v129, v208
	v_cvt_pk_bf16_f32 v112, v15, v216
	v_cvt_pk_bf16_f32 v113, v217, v218
	v_cvt_pk_bf16_f32 v114, v219, v220
	v_cvt_pk_bf16_f32 v115, v221, v222
	v_cvt_pk_bf16_f32 v116, v223, v224
	v_cvt_pk_bf16_f32 v117, v225, v226
	s_waitcnt lgkmcnt(2)
	v_mfma_f32_32x32x16_bf16 v[64:79], v[6:9], v[112:115], v[64:79]
	v_cvt_pk_bf16_f32 v118, v227, v228
	v_cvt_pk_bf16_f32 v119, v229, v230
	ds_read2_b64 v[120:123], v129 offset0:200 offset1:202
	v_max_f32_e32 v202, v96, v97
	v_max3_f32 v202, v202, v98, v99
	s_waitcnt lgkmcnt(1)
	v_mfma_f32_32x32x16_bf16 v[48:63], v[10:13], v[112:115], v[48:63]
	ds_read2_b64 v[112:115], v129 offset0:196 offset1:198
	v_max3_f32 v202, v202, v100, v101
	v_max3_f32 v202, v202, v102, v103
	v_max3_f32 v202, v202, v104, v105
	v_max3_f32 v202, v202, v106, v107
	v_cvt_pk_bf16_f32 v124, v231, v232
	v_cvt_pk_bf16_f32 v125, v233, v234
	v_mfma_f32_32x32x16_bf16 v[64:79], v[2:5], v[116:119], v[64:79]
	v_cvt_pk_bf16_f32 v126, v132, v133
	v_cvt_pk_bf16_f32 v127, v134, v135
	v_max3_f32 v202, v202, v108, v109
	v_max3_f32 v202, v202, v110, v111
	v_max3_f32 v202, v202, v80, v81
	v_max3_f32 v202, v202, v82, v83
	v_max3_f32 v202, v202, v84, v85
	s_waitcnt lgkmcnt(0)
	v_mfma_f32_32x32x16_bf16 v[48:63], v[112:115], v[116:119], v[48:63]
	ds_read2_b64 v[116:119], v128 offset0:136 offset1:138
	v_max3_f32 v202, v202, v86, v87
	v_max3_f32 v202, v202, v88, v89
	v_max3_f32 v202, v202, v90, v91
	v_max3_f32 v202, v202, v92, v93
	v_cvt_pk_bf16_f32 v236, v136, v137
	v_cvt_pk_bf16_f32 v237, v138, v139
	s_waitcnt lgkmcnt(0)
	v_mfma_f32_32x32x16_bf16 v[64:79], v[116:119], v[124:127], v[64:79]
	v_cvt_pk_bf16_f32 v238, v140, v141
	v_cvt_pk_bf16_f32 v239, v142, v143
	v_max3_f32 v202, v202, v94, v95
	v_mov_b32_e32 v203, v202
	s_nop 1
	v_permlane32_swap_b32_e32 v202, v203
	v_mfma_f32_32x32x16_bf16 v[48:63], v[120:123], v[124:127], v[48:63]
	ds_read2_b64 v[124:127], v128 offset0:140 offset1:142
	ds_read2_b64 v[128:131], v129 offset0:204 offset1:206
	v_max_f32_e32 v208, v202, v203
	v_add_f32_e32 v203, 0xc1000000, v208
	v_cmp_gt_f32_e32 vcc, v203, v14
	s_waitcnt lgkmcnt(1)
	v_mfma_f32_32x32x16_bf16 v[64:79], v[124:127], v[236:239], v[64:79]
	s_waitcnt lgkmcnt(0)
	v_mfma_f32_32x32x16_bf16 v[48:63], v[128:131], v[236:239], v[48:63]
	s_cbranch_vccz .LBB0_750
	v_max_f32_e32 v202, v208, v208
	v_max_f32_e32 v203, v14, v14
	v_max_f32_e32 v202, v203, v202
	v_sub_f32_e32 v14, v14, v202
	v_exp_f32_e32 v14, v14
	s_nop 0
	v_mul_f32_e32 v195, v195, v14
	v_pk_mul_f32 v[46:47], v[46:47], v[14:15] op_sel_hi:[1,0]
	v_pk_mul_f32 v[44:45], v[44:45], v[14:15] op_sel_hi:[1,0]
	v_pk_mul_f32 v[42:43], v[42:43], v[14:15] op_sel_hi:[1,0]
	v_pk_mul_f32 v[40:41], v[40:41], v[14:15] op_sel_hi:[1,0]
	v_pk_mul_f32 v[38:39], v[38:39], v[14:15] op_sel_hi:[1,0]
	v_pk_mul_f32 v[36:37], v[36:37], v[14:15] op_sel_hi:[1,0]
	v_pk_mul_f32 v[34:35], v[34:35], v[14:15] op_sel_hi:[1,0]
	v_pk_mul_f32 v[32:33], v[32:33], v[14:15] op_sel_hi:[1,0]
	v_pk_mul_f32 v[30:31], v[30:31], v[14:15] op_sel_hi:[1,0]
	v_pk_mul_f32 v[28:29], v[28:29], v[14:15] op_sel_hi:[1,0]
	v_pk_mul_f32 v[26:27], v[26:27], v[14:15] op_sel_hi:[1,0]
	v_pk_mul_f32 v[24:25], v[24:25], v[14:15] op_sel_hi:[1,0]
	v_pk_mul_f32 v[22:23], v[22:23], v[14:15] op_sel_hi:[1,0]
	v_pk_mul_f32 v[20:21], v[20:21], v[14:15] op_sel_hi:[1,0]
	v_pk_mul_f32 v[18:19], v[18:19], v[14:15] op_sel_hi:[1,0]
	v_pk_mul_f32 v[16:17], v[16:17], v[14:15] op_sel_hi:[1,0]
	v_mov_b32_e32 v14, v202

.LBB0_753:
	s_add_u32 s6, s6, 0x3000
	v_add_f32_e32 v84, v97, v96
	v_add_f32_e32 v85, v216, v15
	s_addc_u32 s7, s7, 0
	v_add_f32_e32 v84, v98, v84
	v_add_f32_e32 v85, v217, v85
	s_add_u32 s0, s0, 0x80
	v_add_f32_e32 v84, v99, v84
	v_add_f32_e32 v85, v218, v85
	s_addc_u32 s1, s1, 0
	v_add_f32_e32 v84, v100, v84
	v_add_f32_e32 v85, v219, v85
	v_add_f32_e32 v84, v101, v84
	v_add_f32_e32 v85, v220, v85
	v_add_f32_e32 v84, v102, v84
	v_add_f32_e32 v85, v221, v85
	v_add_f32_e32 v84, v103, v84
	v_add_f32_e32 v85, v222, v85
	v_add_f32_e32 v84, v104, v84
	v_add_f32_e32 v85, v223, v85
	v_add_f32_e32 v84, v105, v84
	v_add_f32_e32 v85, v224, v85
	v_add_f32_e32 v84, v106, v84
	v_add_f32_e32 v85, v225, v85
	v_add_f32_e32 v84, v107, v84
	v_add_f32_e32 v85, v226, v85
	v_add_f32_e32 v84, v108, v84
	v_add_f32_e32 v85, v227, v85
	v_add_f32_e32 v84, v109, v84
	v_add_f32_e32 v85, v228, v85
	v_add_f32_e32 v84, v110, v84
	v_add_f32_e32 v85, v229, v85
	v_add_f32_e32 v84, v111, v84
	v_add_f32_e32 v85, v230, v85
	v_add_f32_e32 v80, v80, v84
	v_add_f32_e32 v85, v231, v85
	v_add_f32_e32 v6, v6, v80
	v_add_f32_e32 v85, v232, v85
	v_add_f32_e32 v6, v7, v6
	v_add_f32_e32 v85, v233, v85
	v_add_f32_e32 v6, v8, v6
	v_add_f32_e32 v85, v234, v85
	v_add_f32_e32 v6, v9, v6
	v_add_f32_e32 v85, v132, v85
	v_add_f32_e32 v6, v10, v6
	v_add_f32_e32 v85, v133, v85
	v_add_f32_e32 v2, v2, v6
	v_add_f32_e32 v85, v134, v85
	v_add_f32_e32 v2, v3, v2
	v_add_f32_e32 v85, v135, v85
	v_add_f32_e32 v2, v4, v2
	v_add_f32_e32 v85, v136, v85
	v_add_f32_e32 v2, v5, v2
	v_add_f32_e32 v85, v137, v85
	v_add_f32_e32 v2, v11, v2
	v_add_f32_e32 v85, v138, v85
	v_add_f32_e32 v2, v12, v2
	v_add_f32_e32 v85, v139, v85
	v_add_f32_e32 v2, v13, v2
	v_add_f32_e32 v85, v140, v85
	v_add_f32_e32 v2, v81, v2
	v_add_f32_e32 v85, v141, v85
	v_add_f32_e32 v2, v82, v2
	v_add_f32_e32 v85, v142, v85
	v_add_f32_e32 v2, v83, v2
	v_add_f32_e32 v85, v143, v85
	v_add_f32_e32 v195, v195, v2
	v_add_f32_e32 v0, v0, v85
	s_cmp_lg_u32 s6, 0x6c000
	s_waitcnt lgkmcnt(0)
	s_barrier
	s_cbranch_scc0 .LBB0_738
	s_mov_b32 s11, s12
	s_branch .LBB0_746
